# grid barrier: all workgroups poll the TOP arrival counter (released at (gen+1)*nXCD) - removes the last leader's atomic return trip and the generation-word hop
# speedup vs baseline: 1.0048x; 1.0016x over previous
; __device__ __forceinline__ unsigned xb_ld(unsigned* p)              { return __hip_atomic_load(p, __ATOMIC_RELAXED, __HIP_MEMORY_SCOPE_AGENT); }
; __device__ __forceinline__ unsigned xb_add(unsigned* p, unsigned v) { return __hip_atomic_fetch_add(p, v, __ATOMIC_RELAXED, __HIP_MEMORY_SCOPE_AGENT); }
; #define XB_SPIN(cond, bar) do { unsigned _sp = 0; while (cond) { __builtin_amdgcn_s_sleep(1); \
;     if ((++_sp & 255u) == 0u) { if (xb_ld(&(bar)[XB_TMO])) break; if (_sp > XB_SPIN_CAP) { atomicAdd(&(bar)[XB_TMO], 1u); break; } } } } while (0)
; __device__ __forceinline__ void xcd_barrier(const XcdBarrier& b) {
;     ...
;         const unsigned old = xb_add(&bar[XB_XSUB(b.x)], 1u);
;         const unsigned gen = old / nloc;
;         if (old + 1u == (gen + 1u) * nloc) {
;             __builtin_amdgcn_fence(__ATOMIC_RELEASE, "agent");
;             asm volatile("s_waitcnt vmcnt(0)" ::: "memory");
;             const unsigned og = xb_add(&bar[XB_TOP], 1u);
;             const unsigned tg = og / nx;
;             if (og + 1u == (tg + 1u) * nx) xb_add(&bar[XB_TOPGEN], 1u);
;             else XB_SPIN(xb_ld(&bar[XB_TOPGEN]) == tg, bar);
.LBB0_1396:
	s_or_b64 exec, exec, s[40:41]
	v_cvt_f32_u32_e32 v4, v2
	s_waitcnt vmcnt(0)
	buffer_inv sc1
	v_readfirstlane_b32 s29, v3
	v_sub_u32_e32 v3, 0, v2
	v_rcp_iflag_f32_e32 v4, v4
	v_add_u32_e32 v5, s29, v1
	v_mul_f32_e32 v4, 0x4f7ffffe, v4
	v_cvt_u32_f32_e32 v4, v4
	v_mul_lo_u32 v1, v3, v4
	v_mul_hi_u32 v1, v4, v1
	v_add_u32_e32 v1, v4, v1
	v_mul_hi_u32 v1, v5, v1
	v_mul_lo_u32 v3, v1, v2
	v_sub_u32_e32 v3, v5, v3
	v_add_u32_e32 v4, 1, v1
	v_cmp_ge_u32_e32 vcc, v3, v2
	s_nop 1
	v_cndmask_b32_e32 v1, v1, v4, vcc
	v_sub_u32_e32 v4, v3, v2
	v_cndmask_b32_e32 v3, v3, v4, vcc
	v_add_u32_e32 v4, 1, v1
	v_cmp_ge_u32_e32 vcc, v3, v2
	v_add_u32_e32 v3, 1, v5
	s_nop 0
	v_cndmask_b32_e32 v1, v1, v4, vcc
	v_mul_lo_u32 v4, v2, v1
	v_add_u32_e32 v2, v4, v2
	v_cmp_ne_u32_e32 vcc, v3, v2
	s_and_saveexec_b64 s[34:35], vcc
	s_xor_b64 s[40:41], exec, s[34:35]
	s_cbranch_execz .LBB0_1410
	v_add_u32_e32 v4, 1, v1
	v_mul_lo_u32 v4, v4, v0
	v_readlane_b32 s34, v252, 40
	v_readlane_b32 s35, v252, 41
	s_waitcnt lgkmcnt(0)
	s_nop 3
	global_load_dword v0, v65, s[34:35] sc1
	s_waitcnt vmcnt(0)
	v_cmp_lt_u32_e32 vcc, v0, v4
	s_and_saveexec_b64 s[42:43], vcc
	s_cbranch_execz .LBB0_1409
	s_mov_b32 s29, 1
	s_mov_b64 s[44:45], 0
	s_branch .LBB0_1400

; __device__ __forceinline__ unsigned xb_ld(unsigned* p)              { return __hip_atomic_load(p, __ATOMIC_RELAXED, __HIP_MEMORY_SCOPE_AGENT); }
; __device__ __forceinline__ unsigned xb_add(unsigned* p, unsigned v) { return __hip_atomic_fetch_add(p, v, __ATOMIC_RELAXED, __HIP_MEMORY_SCOPE_AGENT); }
; #define XB_SPIN(cond, bar) do { unsigned _sp = 0; while (cond) { __builtin_amdgcn_s_sleep(1); \
;     if ((++_sp & 255u) == 0u) { if (xb_ld(&(bar)[XB_TMO])) break; if (_sp > XB_SPIN_CAP) { atomicAdd(&(bar)[XB_TMO], 1u); break; } } } } while (0)
; __device__ __forceinline__ void xcd_barrier(const XcdBarrier& b) {
;     ...
;             const unsigned og = xb_add(&bar[XB_TOP], 1u);
;             const unsigned tg = og / nx;
;             if (og + 1u == (tg + 1u) * nx) xb_add(&bar[XB_TOPGEN], 1u);
;             else XB_SPIN(xb_ld(&bar[XB_TOPGEN]) == tg, bar);
.LBB0_1402:
	v_readlane_b32 s34, v252, 40
	v_readlane_b32 s35, v252, 41
	s_add_i32 s29, s29, 1
	s_mov_b64 s[50:51], -1
	s_nop 2
	global_load_dword v0, v65, s[34:35] sc1
	s_waitcnt vmcnt(0)
	v_cmp_ge_u32_e32 vcc, v0, v4
	s_orn2_b64 s[48:49], vcc, exec
	s_branch .LBB0_1399

; __device__ __forceinline__ unsigned xb_ld(unsigned* p)              { return __hip_atomic_load(p, __ATOMIC_RELAXED, __HIP_MEMORY_SCOPE_AGENT); }
; __device__ __forceinline__ unsigned xb_add(unsigned* p, unsigned v) { return __hip_atomic_fetch_add(p, v, __ATOMIC_RELAXED, __HIP_MEMORY_SCOPE_AGENT); }
; #define XB_SPIN(cond, bar) do { unsigned _sp = 0; while (cond) { __builtin_amdgcn_s_sleep(1); \
;     if ((++_sp & 255u) == 0u) { if (xb_ld(&(bar)[XB_TMO])) break; if (_sp > XB_SPIN_CAP) { atomicAdd(&(bar)[XB_TMO], 1u); break; } } } } while (0)
; __device__ __forceinline__ void xcd_barrier(const XcdBarrier& b) {
;     ...
;             const unsigned og = xb_add(&bar[XB_TOP], 1u);
;             const unsigned tg = og / nx;
;             if (og + 1u == (tg + 1u) * nx) xb_add(&bar[XB_TOPGEN], 1u);
;             else XB_SPIN(xb_ld(&bar[XB_TOPGEN]) == tg, bar);
.LBB0_1413:
	s_or_b64 exec, exec, s[42:43]
	s_waitcnt vmcnt(0)
	v_readfirstlane_b32 s29, v2
	v_cvt_f32_u32_e32 v2, v0
	v_sub_u32_e32 v3, 0, v0
	v_add_u32_e32 v1, s29, v1
	v_readlane_b32 s34, v252, 42
	v_rcp_iflag_f32_e32 v2, v2
	v_readlane_b32 s35, v252, 43
	s_mov_b64 s[42:43], -1
	v_mul_f32_e32 v2, 0x4f7ffffe, v2
	v_cvt_u32_f32_e32 v2, v2
	v_mul_lo_u32 v3, v3, v2
	v_mul_hi_u32 v3, v2, v3
	v_add_u32_e32 v2, v2, v3
	v_mul_hi_u32 v2, v1, v2
	v_mul_lo_u32 v3, v2, v0
	v_sub_u32_e32 v3, v1, v3
	v_cmp_ge_u32_e32 vcc, v3, v0
	v_add_u32_e32 v4, 1, v2
	v_add_u32_e32 v1, 1, v1
	v_cndmask_b32_e32 v2, v2, v4, vcc
	v_sub_u32_e32 v4, v3, v0
	v_cndmask_b32_e32 v3, v3, v4, vcc
	v_cmp_ge_u32_e32 vcc, v3, v0
	v_add_u32_e32 v3, 1, v2
	s_nop 0
	v_cndmask_b32_e32 v2, v2, v3, vcc
	v_mul_lo_u32 v3, v0, v2
	v_add_u32_e32 v0, v3, v0
	v_mov_b32_e32 v4, v0
	v_cmp_ne_u32_e32 vcc, v1, v0
	v_mov_b64_e32 v[0:1], s[34:35]
	s_and_saveexec_b64 s[40:41], vcc
	s_cbranch_execz .LBB0_1426
	v_readlane_b32 s34, v252, 40
	v_readlane_b32 s35, v252, 41
	s_mov_b64 s[44:45], 0
	s_nop 3
	global_load_dword v0, v65, s[34:35] sc1
	s_waitcnt vmcnt(0)
	v_cmp_lt_u32_e32 vcc, v0, v4
	s_and_saveexec_b64 s[42:43], vcc
	s_cbranch_execz .LBB0_1425
	s_mov_b32 s29, 1
	s_branch .LBB0_1417

; __device__ __forceinline__ unsigned xb_ld(unsigned* p)              { return __hip_atomic_load(p, __ATOMIC_RELAXED, __HIP_MEMORY_SCOPE_AGENT); }
; __device__ __forceinline__ unsigned xb_add(unsigned* p, unsigned v) { return __hip_atomic_fetch_add(p, v, __ATOMIC_RELAXED, __HIP_MEMORY_SCOPE_AGENT); }
; #define XB_SPIN(cond, bar) do { unsigned _sp = 0; while (cond) { __builtin_amdgcn_s_sleep(1); \
;     if ((++_sp & 255u) == 0u) { if (xb_ld(&(bar)[XB_TMO])) break; if (_sp > XB_SPIN_CAP) { atomicAdd(&(bar)[XB_TMO], 1u); break; } } } } while (0)
; __device__ __forceinline__ void xcd_barrier(const XcdBarrier& b) {
;     ...
;             const unsigned og = xb_add(&bar[XB_TOP], 1u);
;             const unsigned tg = og / nx;
;             if (og + 1u == (tg + 1u) * nx) xb_add(&bar[XB_TOPGEN], 1u);
;             else XB_SPIN(xb_ld(&bar[XB_TOPGEN]) == tg, bar);
.LBB0_1451:
	s_or_b64 exec, exec, s[38:39]
	v_cvt_f32_u32_e32 v4, v2
	s_waitcnt vmcnt(0)
	buffer_inv sc1
	v_readfirstlane_b32 s29, v3
	v_sub_u32_e32 v3, 0, v2
	v_rcp_iflag_f32_e32 v4, v4
	v_add_u32_e32 v5, s29, v1
	v_mul_f32_e32 v4, 0x4f7ffffe, v4
	v_cvt_u32_f32_e32 v4, v4
	v_mul_lo_u32 v1, v3, v4
	v_mul_hi_u32 v1, v4, v1
	v_add_u32_e32 v1, v4, v1
	v_mul_hi_u32 v1, v5, v1
	v_mul_lo_u32 v3, v1, v2
	v_sub_u32_e32 v3, v5, v3
	v_add_u32_e32 v4, 1, v1
	v_cmp_ge_u32_e32 vcc, v3, v2
	s_nop 1
	v_cndmask_b32_e32 v1, v1, v4, vcc
	v_sub_u32_e32 v4, v3, v2
	v_cndmask_b32_e32 v3, v3, v4, vcc
	v_add_u32_e32 v4, 1, v1
	v_cmp_ge_u32_e32 vcc, v3, v2
	v_add_u32_e32 v3, 1, v5
	s_nop 0
	v_cndmask_b32_e32 v1, v1, v4, vcc
	v_mul_lo_u32 v4, v2, v1
	v_add_u32_e32 v2, v4, v2
	v_cmp_ne_u32_e32 vcc, v3, v2
	s_and_saveexec_b64 s[34:35], vcc
	s_xor_b64 s[38:39], exec, s[34:35]
	s_cbranch_execz .LBB0_1465
	v_add_u32_e32 v4, 1, v1
	v_mul_lo_u32 v4, v4, v0
	v_readlane_b32 s34, v252, 40
	v_readlane_b32 s35, v252, 41
	s_waitcnt lgkmcnt(0)
	s_nop 3
	global_load_dword v0, v65, s[34:35] sc1
	s_waitcnt vmcnt(0)
	v_cmp_lt_u32_e32 vcc, v0, v4
	s_and_saveexec_b64 s[40:41], vcc
	s_cbranch_execz .LBB0_1464
	s_mov_b32 s29, 1
	s_mov_b64 s[42:43], 0
	s_branch .LBB0_1455

; __device__ __forceinline__ unsigned xb_ld(unsigned* p)              { return __hip_atomic_load(p, __ATOMIC_RELAXED, __HIP_MEMORY_SCOPE_AGENT); }
; __device__ __forceinline__ unsigned xb_add(unsigned* p, unsigned v) { return __hip_atomic_fetch_add(p, v, __ATOMIC_RELAXED, __HIP_MEMORY_SCOPE_AGENT); }
; #define XB_SPIN(cond, bar) do { unsigned _sp = 0; while (cond) { __builtin_amdgcn_s_sleep(1); \
;     if ((++_sp & 255u) == 0u) { if (xb_ld(&(bar)[XB_TMO])) break; if (_sp > XB_SPIN_CAP) { atomicAdd(&(bar)[XB_TMO], 1u); break; } } } } while (0)
; __device__ __forceinline__ void xcd_barrier(const XcdBarrier& b) {
;     ...
;             const unsigned og = xb_add(&bar[XB_TOP], 1u);
;             const unsigned tg = og / nx;
;             if (og + 1u == (tg + 1u) * nx) xb_add(&bar[XB_TOPGEN], 1u);
;             else XB_SPIN(xb_ld(&bar[XB_TOPGEN]) == tg, bar);
.LBB0_1457:
	v_readlane_b32 s34, v252, 40
	v_readlane_b32 s35, v252, 41
	s_add_i32 s29, s29, 1
	s_mov_b64 s[48:49], -1
	s_nop 2
	global_load_dword v0, v65, s[34:35] sc1
	s_waitcnt vmcnt(0)
	v_cmp_ge_u32_e32 vcc, v0, v4
	s_orn2_b64 s[46:47], vcc, exec
	s_branch .LBB0_1454

; __device__ __forceinline__ unsigned xb_ld(unsigned* p)              { return __hip_atomic_load(p, __ATOMIC_RELAXED, __HIP_MEMORY_SCOPE_AGENT); }
; __device__ __forceinline__ unsigned xb_add(unsigned* p, unsigned v) { return __hip_atomic_fetch_add(p, v, __ATOMIC_RELAXED, __HIP_MEMORY_SCOPE_AGENT); }
; #define XB_SPIN(cond, bar) do { unsigned _sp = 0; while (cond) { __builtin_amdgcn_s_sleep(1); \
;     if ((++_sp & 255u) == 0u) { if (xb_ld(&(bar)[XB_TMO])) break; if (_sp > XB_SPIN_CAP) { atomicAdd(&(bar)[XB_TMO], 1u); break; } } } } while (0)
; __device__ __forceinline__ void xcd_barrier(const XcdBarrier& b) {
;     ...
;             const unsigned og = xb_add(&bar[XB_TOP], 1u);
;             const unsigned tg = og / nx;
;             if (og + 1u == (tg + 1u) * nx) xb_add(&bar[XB_TOPGEN], 1u);
;             else XB_SPIN(xb_ld(&bar[XB_TOPGEN]) == tg, bar);
.LBB0_1468:
	s_or_b64 exec, exec, s[40:41]
	s_waitcnt vmcnt(0)
	v_readfirstlane_b32 s29, v2
	v_cvt_f32_u32_e32 v2, v0
	v_sub_u32_e32 v3, 0, v0
	v_add_u32_e32 v1, s29, v1
	v_readlane_b32 s34, v252, 42
	v_rcp_iflag_f32_e32 v2, v2
	v_readlane_b32 s35, v252, 43
	s_mov_b64 s[40:41], -1
	v_mul_f32_e32 v2, 0x4f7ffffe, v2
	v_cvt_u32_f32_e32 v2, v2
	v_mul_lo_u32 v3, v3, v2
	v_mul_hi_u32 v3, v2, v3
	v_add_u32_e32 v2, v2, v3
	v_mul_hi_u32 v2, v1, v2
	v_mul_lo_u32 v3, v2, v0
	v_sub_u32_e32 v3, v1, v3
	v_cmp_ge_u32_e32 vcc, v3, v0
	v_add_u32_e32 v4, 1, v2
	v_add_u32_e32 v1, 1, v1
	v_cndmask_b32_e32 v2, v2, v4, vcc
	v_sub_u32_e32 v4, v3, v0
	v_cndmask_b32_e32 v3, v3, v4, vcc
	v_cmp_ge_u32_e32 vcc, v3, v0
	v_add_u32_e32 v3, 1, v2
	s_nop 0
	v_cndmask_b32_e32 v2, v2, v3, vcc
	v_mul_lo_u32 v3, v0, v2
	v_add_u32_e32 v0, v3, v0
	v_mov_b32_e32 v4, v0
	v_cmp_ne_u32_e32 vcc, v1, v0
	v_mov_b64_e32 v[0:1], s[34:35]
	s_and_saveexec_b64 s[38:39], vcc
	s_cbranch_execz .LBB0_1480
	v_readlane_b32 s34, v252, 40
	v_readlane_b32 s35, v252, 41
	s_mov_b64 s[42:43], 0
	s_nop 3
	global_load_dword v0, v65, s[34:35] sc1
	s_waitcnt vmcnt(0)
	v_cmp_lt_u32_e32 vcc, v0, v4
	s_and_saveexec_b64 s[40:41], vcc
	s_cbranch_execz .LBB0_1479
	s_mov_b32 s29, 1
	s_branch .LBB0_1472
